# static priority for waves 0-3 over the whole attention item
# speedup vs baseline: 1.0053x; 1.0042x over previous
.LBB0_590:
	s_setprio 0
	v_mov_b32_e32 v2, v238
	s_nop 1
	v_permlane32_swap_b32_e32 v238, v2
	v_add_f32_e32 v2, v238, v2
	v_div_scale_f32 v38, s[74:75], v2, v2, 1.0
	v_rcp_f32_e32 v39, v38
	v_lshlrev_b64 v[36:37], 9, v[220:221]
	v_lshl_add_u64 v[36:37], v[36:37], 1, s[68:69]
	v_lshl_add_u64 v[36:37], v[36:37], 0, s[48:49]
	v_fma_f32 v40, -v38, v39, 1.0
	v_fmac_f32_e32 v39, v40, v39
	v_div_scale_f32 v40, vcc, 1.0, v2, 1.0
	v_mul_f32_e32 v41, v40, v39
	v_fma_f32 v42, -v38, v41, v40
	v_fmac_f32_e32 v41, v42, v39
	v_fma_f32 v38, -v38, v41, v40
	v_div_fmas_f32 v38, v38, v39, v41
	v_div_fixup_f32 v2, v38, v2, 1.0
	v_pk_mul_f32 v[4:5], v[4:5], v[2:3] op_sel_hi:[1,0]
	v_lshlrev_b32_e32 v38, 16, v218
	v_and_b32_e32 v39, 0xffff0000, v218
	v_pk_mul_f32 v[4:5], v[4:5], v[38:39]
	v_pk_mul_f32 v[6:7], v[6:7], v[2:3] op_sel_hi:[1,0]
	v_lshlrev_b32_e32 v38, 16, v219
	v_and_b32_e32 v39, 0xffff0000, v219
	v_pk_mul_f32 v[6:7], v[6:7], v[38:39]
	v_mov_b32_e32 v183, v3
	v_cvt_pk_bf16_f32 v4, v4, v5
	v_cvt_pk_bf16_f32 v5, v6, v7
	v_lshl_add_u64 v[6:7], v[36:37], 0, v[182:183]
	global_store_dwordx2 v[6:7], v[4:5], off
	v_pk_mul_f32 v[4:5], v[8:9], v[2:3] op_sel_hi:[1,0]
	v_lshlrev_b32_e32 v8, 16, v216
	v_and_b32_e32 v9, 0xffff0000, v216
	v_pk_mul_f32 v[4:5], v[4:5], v[8:9]
	v_pk_mul_f32 v[8:9], v[10:11], v[2:3] op_sel_hi:[1,0]
	v_lshlrev_b32_e32 v10, 16, v217
	v_and_b32_e32 v11, 0xffff0000, v217
	v_pk_mul_f32 v[8:9], v[8:9], v[10:11]
	v_cvt_pk_bf16_f32 v4, v4, v5
	v_cvt_pk_bf16_f32 v5, v8, v9
	global_store_dwordx2 v[6:7], v[4:5], off offset:16
	v_pk_mul_f32 v[4:5], v[12:13], v[2:3] op_sel_hi:[1,0]
	v_lshlrev_b32_e32 v8, 16, v214
	v_and_b32_e32 v9, 0xffff0000, v214
	v_pk_mul_f32 v[4:5], v[4:5], v[8:9]
	v_pk_mul_f32 v[8:9], v[14:15], v[2:3] op_sel_hi:[1,0]
	v_lshlrev_b32_e32 v10, 16, v215
	v_and_b32_e32 v11, 0xffff0000, v215
	v_pk_mul_f32 v[8:9], v[8:9], v[10:11]
	v_cvt_pk_bf16_f32 v4, v4, v5
	v_cvt_pk_bf16_f32 v5, v8, v9
	global_store_dwordx2 v[6:7], v[4:5], off offset:32
	v_pk_mul_f32 v[4:5], v[16:17], v[2:3] op_sel_hi:[1,0]
	v_lshlrev_b32_e32 v8, 16, v212
	v_and_b32_e32 v9, 0xffff0000, v212
	v_pk_mul_f32 v[4:5], v[4:5], v[8:9]
	v_pk_mul_f32 v[8:9], v[18:19], v[2:3] op_sel_hi:[1,0]
	v_lshlrev_b32_e32 v10, 16, v213
	v_and_b32_e32 v11, 0xffff0000, v213
	v_pk_mul_f32 v[8:9], v[8:9], v[10:11]
	v_cvt_pk_bf16_f32 v4, v4, v5
	v_cvt_pk_bf16_f32 v5, v8, v9
	global_store_dwordx2 v[6:7], v[4:5], off offset:48
	v_pk_mul_f32 v[4:5], v[20:21], v[2:3] op_sel_hi:[1,0]
	v_lshlrev_b32_e32 v8, 16, v210
	v_and_b32_e32 v9, 0xffff0000, v210
	v_pk_mul_f32 v[4:5], v[4:5], v[8:9]
	v_pk_mul_f32 v[8:9], v[22:23], v[2:3] op_sel_hi:[1,0]
	v_lshlrev_b32_e32 v10, 16, v211
	v_and_b32_e32 v11, 0xffff0000, v211
	v_pk_mul_f32 v[8:9], v[8:9], v[10:11]
	v_cvt_pk_bf16_f32 v4, v4, v5
	v_cvt_pk_bf16_f32 v5, v8, v9
	global_store_dwordx2 v[6:7], v[4:5], off offset:64
	v_pk_mul_f32 v[4:5], v[24:25], v[2:3] op_sel_hi:[1,0]
	v_lshlrev_b32_e32 v8, 16, v208
	v_and_b32_e32 v9, 0xffff0000, v208
	v_pk_mul_f32 v[4:5], v[4:5], v[8:9]
	v_pk_mul_f32 v[8:9], v[26:27], v[2:3] op_sel_hi:[1,0]
	v_lshlrev_b32_e32 v10, 16, v209
	v_and_b32_e32 v11, 0xffff0000, v209
	v_pk_mul_f32 v[8:9], v[8:9], v[10:11]
	v_cvt_pk_bf16_f32 v4, v4, v5
	v_cvt_pk_bf16_f32 v5, v8, v9
	global_store_dwordx2 v[6:7], v[4:5], off offset:80
	v_pk_mul_f32 v[4:5], v[28:29], v[2:3] op_sel_hi:[1,0]
	v_lshlrev_b32_e32 v8, 16, v206
	v_and_b32_e32 v9, 0xffff0000, v206
	v_pk_mul_f32 v[4:5], v[4:5], v[8:9]
	v_pk_mul_f32 v[8:9], v[30:31], v[2:3] op_sel_hi:[1,0]
	v_lshlrev_b32_e32 v10, 16, v207
	v_and_b32_e32 v11, 0xffff0000, v207
	v_pk_mul_f32 v[8:9], v[8:9], v[10:11]
	v_cvt_pk_bf16_f32 v4, v4, v5
	v_cvt_pk_bf16_f32 v5, v8, v9
	global_store_dwordx2 v[6:7], v[4:5], off offset:96
	v_pk_mul_f32 v[4:5], v[32:33], v[2:3] op_sel_hi:[1,0]
	v_lshlrev_b32_e32 v8, 16, v204
	v_and_b32_e32 v9, 0xffff0000, v204
	v_pk_mul_f32 v[4:5], v[4:5], v[8:9]
	v_pk_mul_f32 v[8:9], v[34:35], v[2:3] op_sel_hi:[1,0]
	v_lshlrev_b32_e32 v10, 16, v205
	v_and_b32_e32 v11, 0xffff0000, v205
	v_pk_mul_f32 v[8:9], v[8:9], v[10:11]
	v_cvt_pk_bf16_f32 v4, v4, v5
	v_cvt_pk_bf16_f32 v5, v8, v9
	global_store_dwordx2 v[6:7], v[4:5], off offset:112

.LBB0_623:
	s_and_b64 vcc, exec, s[74:75]
	s_cbranch_vccz .LBB0_591
	v_readfirstlane_b32 s76, v0
	s_bitcmp1_b32 s76, 8
	s_cbranch_scc1 .Latt_item_prio_skip
	s_setprio 1
.Latt_item_prio_skip:
	s_and_b32 s48, s84, 63
	s_lshr_b32 s78, s84, 6
	s_sub_i32 s79, 15, s78
	s_mul_i32 s76, s48, 0xc0000
	s_add_u32 s74, s87, s76
	s_addc_u32 s75, s88, 0
	s_add_u32 s76, s89, s76
	s_addc_u32 s77, s91, 0
	s_lshl_b32 s85, s48, 19
	v_lshl_add_u32 v4, s79, 8, v157
	s_lshl_b32 s48, s84, 9
	s_and_b32 s48, s48, 0x7000
	v_ashrrev_i32_e32 v5, 31, v4
	v_or_b32_e32 v2, v4, v156
	v_lshl_add_u64 v[4:5], v[4:5], 0, s[48:49]
	v_or_b32_e32 v221, v5, v1
	v_or_b32_e32 v220, v4, v156
	s_lshl_b32 s48, s84, 6
	v_mov_b64_e32 v[6:7], s[74:75]
	v_lshlrev_b64 v[4:5], 10, v[220:221]
	s_and_b32 s48, s48, 0x1c0
	v_mad_i64_i32 v[6:7], s[74:75], v2, s86, v[6:7]
	v_lshl_add_u64 v[4:5], s[66:67], 0, v[4:5]
	s_lshl_b32 s48, s48, 1
	v_lshlrev_b32_e32 v222, 1, v158
	v_mov_b32_e32 v223, v3
	v_lshl_add_u64 v[4:5], v[4:5], 0, s[48:49]
	v_mov_b32_e32 v183, v3
	s_add_u32 s74, s92, s85
	v_lshl_add_u64 v[6:7], v[6:7], 0, v[222:223]
	v_lshl_add_u64 v[4:5], v[4:5], 0, v[182:183]
	s_addc_u32 s75, s93, 0
	v_mov_b32_e32 v191, v3
	global_load_dwordx4 v[132:135], v[6:7], off
	global_load_dwordx4 v[136:139], v[6:7], off offset:32
	global_load_dwordx4 v[140:143], v[6:7], off offset:64
	global_load_dwordx4 v[144:147], v[6:7], off offset:96
	global_load_dwordx4 v[148:151], v[6:7], off offset:128
	global_load_dwordx4 v[152:155], v[6:7], off offset:160
	global_load_dwordx2 v[218:219], v[4:5], off
	global_load_dwordx2 v[216:217], v[4:5], off offset:16
	global_load_dwordx2 v[214:215], v[4:5], off offset:32
	global_load_dwordx2 v[212:213], v[4:5], off offset:48
	global_load_dwordx2 v[210:211], v[4:5], off offset:64
	global_load_dwordx2 v[208:209], v[4:5], off offset:80
	global_load_dwordx2 v[206:207], v[4:5], off offset:96
	global_load_dwordx2 v[204:205], v[4:5], off offset:112
	v_lshl_add_u64 v[8:9], s[76:77], 0, v[190:191]
	v_mov_b32_e32 v193, v3
	v_lshl_add_u64 v[10:11], s[74:75], 0, v[164:165]
	v_mov_b32_e32 v195, v3
	v_mov_b32_e32 v185, v3
	v_lshl_add_u64 v[8:9], v[8:9], 0, v[192:193]
	v_lshl_add_u64 v[10:11], v[10:11], 0, v[194:195]
	v_add_u32_e32 v2, 0, v245
	v_lshl_add_u64 v[4:5], s[76:77], 0, v[184:185]
	v_mov_b32_e32 v187, v3
	v_lshl_add_u64 v[6:7], s[76:77], 0, v[162:163]
	v_cndmask_b32_e64 v9, v11, v9, s[40:41]
	v_cndmask_b32_e64 v8, v10, v8, s[40:41]
	v_lshl_add_u64 v[10:11], s[76:77], 0, v[168:169]
	v_readfirstlane_b32 s76, v2
	v_add_u32_e32 v2, 0, v246
	v_lshl_add_u64 v[4:5], v[4:5], 0, v[186:187]
	v_mov_b32_e32 v189, v3
	s_mov_b32 m0, s76
	v_readfirstlane_b32 s76, v2
	v_add_u32_e32 v2, 0, v251
	v_lshl_add_u64 v[6:7], v[6:7], 0, v[188:189]
	v_mov_b32_e32 v197, v3
	v_lshl_add_u64 v[12:13], s[74:75], 0, v[166:167]
	v_mov_b32_e32 v199, v3
	s_barrier
	global_load_lds_dwordx4 v[4:5], off
	s_mov_b32 m0, s76
	v_readfirstlane_b32 s76, v2
	v_add_u32_e32 v2, 0, v252
	v_lshl_add_u64 v[10:11], v[10:11], 0, v[196:197]
	v_lshl_add_u64 v[12:13], v[12:13], 0, v[198:199]
	global_load_lds_dwordx4 v[6:7], off
	s_mov_b32 m0, s76
	v_readfirstlane_b32 s76, v2
	v_cndmask_b32_e64 v11, v13, v11, s[42:43]
	v_cndmask_b32_e64 v10, v12, v10, s[42:43]
	global_load_lds_dwordx4 v[8:9], off
	s_mov_b32 m0, s76
	v_lshl_add_u64 v[12:13], s[74:75], 0, v[170:171]
	global_load_lds_dwordx4 v[10:11], off
	v_mov_b32_e32 v201, v3
	v_lshl_add_u64 v[224:225], v[12:13], 0, v[200:201]
	s_and_saveexec_b64 s[76:77], s[36:37]
	s_cbranch_execz .LBB0_626
	v_add_u32_e32 v2, 0, v247
	v_add_u32_e32 v2, 0x6800, v2
	s_nop 0
	v_readfirstlane_b32 s85, v2
	s_mov_b32 m0, s85
	s_nop 0
	global_load_lds_dwordx4 v[224:225], off
	v_lshl_add_u64 v[224:225], v[224:225], 0, s[70:71]
